# hgrn unit loops: loop-top vmcnt waits (which drained the previous unit's stores every unit) removed; the pre-header waits once for the first unit's loads
# baseline (speedup 1.0000x reference)
; template <int WHICH>
; __device__ __forceinline__ HgRaw hg_load(KP& P_, int l, int u, int tid) {
;     const bf16_t* proj = (const bf16_t*)(p.ws + WS_PROJ);
;     const int idx = u - 780, bc = idx / 6, h = idx - bc * 6, t = tid >> 3, k0 = (tid & 7) * 8; const size_t row = (size_t)bc * 64 + t;
;     HgRaw r; r.q = (u32x4){0u, 0u, 0u, 0u};
;     if (WHICH) r.q = *(const u32x4*)(proj + row * NPROJ + h * 64 + k0);
;     r.f = *(const u32x4*)(proj + row * NPROJ + C_F + h * 64 + k0);
;     r.i = *(const u32x4*)(proj + row * NPROJ + C_I + h * 64 + k0);
;     const float* lbv = (const float*)(p.ws + TBL(T_LB, l)) + h * 64 + k0; r.lb0 = *(const f32x4*)lbv; r.lb1 = *(const f32x4*)(lbv + 4);
;     return r;
; }
; template <int WHICH>
; __device__ void phase_mix_dyn(LAS unsigned char* lds, KP& P0, int l0) {
;     ...
;     if (u >= NMIXU) return;
;     HgRaw nxt; { KPtr P_ = P0; asm volatile("" : "+s"(P_.q)); nxt = hg_load<WHICH>(P_, l0, u, tid0); }
.LBB0_479:
	s_cmpk_gt_u32 s20, 0x923
	s_cbranch_scc1 .LBB0_502
	s_mov_b64 s[6:7], s[30:31]
	s_load_dwordx2 s[6:7], s[6:7], 0xe8
	s_add_i32 s12, s20, 0xfffffcf4
	s_mul_i32 s13, s12, 0xaaab
	s_lshr_b32 s13, s13, 18
	v_ashrrev_i32_e32 v2, 3, v138
	v_lshlrev_b32_e32 v0, 3, v138
	s_mul_i32 s14, s13, -6
	s_waitcnt vmcnt(0)
	v_and_b32_e32 v72, 56, v0
	v_lshl_add_u32 v0, s13, 6, v2
	s_waitcnt lgkmcnt(0)
	v_mov_b64_e32 v[8:9], s[6:7]
	s_add_i32 s14, s14, s12
	v_mad_i64_i32 v[8:9], s[12:13], v0, s9, v[8:9]
	s_lshl_b32 s12, s14, 6
	v_readlane_b32 s14, v255, 25
	v_readlane_b32 s15, v255, 26
	s_mov_b32 s22, s14
	s_ashr_i32 s13, s12, 31
	s_mul_i32 s15, s22, 0x44800
	s_mul_hi_i32 s14, s14, 0x44800
	s_add_u32 s15, s6, s15
	s_addc_u32 s14, s7, s14
	s_lshl_b64 s[6:7], s[12:13], 2
	v_lshl_add_u64 v[8:9], s[12:13], 1, v[8:9]
	v_lshlrev_b32_e32 v0, 1, v72
	s_add_u32 s6, s15, s6
	v_lshl_add_u64 v[8:9], v[8:9], 0, v[0:1]
	s_addc_u32 s7, s14, s7
	v_lshlrev_b32_e32 v0, 2, v72
	global_load_dwordx4 v[52:55], v[8:9], off
	global_load_dwordx4 v[68:71], v[8:9], off offset:768
	global_load_dwordx4 v[56:59], v[8:9], off offset:1536
	v_lshl_add_u64 v[8:9], s[6:7], 0, v[0:1]
	s_mov_b64 s[6:7], 0xef04800
	v_lshl_add_u64 v[10:11], v[8:9], 0, s[6:7]
	v_add_co_u32_e32 v8, vcc, 0xef04000, v8
	v_ashrrev_i32_e32 v3, 31, v2
	s_nop 0
	v_addc_co_u32_e32 v9, vcc, 0, v9, vcc
	global_load_dwordx4 v[64:67], v[8:9], off offset:2048
	global_load_dwordx4 v[60:63], v[10:11], off offset:16
	s_waitcnt vmcnt(0)
	s_branch .LBB0_483

; template <int WHICH>
; __device__ void phase_mix_dyn(LAS unsigned char* lds, KP& P0, int l0) {
;     ...
;     for (;;) {
;         if (tid0 == 0) { n1 = n2; n2 = (int)__hip_atomic_fetch_add(ctr, 1u, __ATOMIC_RELAXED, __HIP_MEMORY_SCOPE_AGENT); }
;         KPtr P_ = P0; int l = l0; asm volatile("" : "+s"(P_.q), "+s"(l));
;         const HgRaw cur = nxt;
;         if (un < NMIXU) nxt = hg_load<WHICH>(P_, l, un, tid0);
;         if (WHICH == 0) hgrn_a_unit(lds, P_, l, (u - 780) / 6, (u - 780) % 6, cur);
;         else            hgrn_c_unit(lds, P_, l, (u - 780) / 6, (u - 780) % 6, cur);
.LBB0_483:
	v_readlane_b32 s6, v255, 25
	s_mov_b32 s12, s6
	s_mov_b64 s[46:47], s[30:31]
	s_load_dwordx2 s[42:43], s[46:47], 0xe8
	s_cmpk_lt_i32 s21, 0x924
	v_readlane_b32 s7, v255, 26
	s_cselect_b64 s[24:25], -1, 0
	s_cmpk_gt_i32 s21, 0x923
	s_cselect_b64 s[6:7], -1, 0
	v_mov_b64_e32 v[8:9], v[52:53]
	v_mov_b64_e32 v[12:13], v[68:69]
	v_mov_b64_e32 v[20:21], v[56:57]
	v_mov_b64_e32 v[16:17], v[64:65]
	s_and_saveexec_b64 s[14:15], s[40:41]
	s_cbranch_execz .Lhg_tk_c
	v_mov_b32_e32 v137, v136
	v_readlane_b32 s22, v255, 30
	v_readlane_b32 s23, v255, 31
	s_nop 4
	global_atomic_add v136, v1, v203, s[22:23] sc0

; template <int WHICH>
; __device__ __forceinline__ HgRaw hg_load(KP& P_, int l, int u, int tid) {
;     const bf16_t* proj = (const bf16_t*)(p.ws + WS_PROJ);
;     const int idx = u - 780, bc = idx / 6, h = idx - bc * 6, t = tid >> 3, k0 = (tid & 7) * 8; const size_t row = (size_t)bc * 64 + t;
;     HgRaw r; r.q = (u32x4){0u, 0u, 0u, 0u};
;     if (WHICH) r.q = *(const u32x4*)(proj + row * NPROJ + h * 64 + k0);
;     r.f = *(const u32x4*)(proj + row * NPROJ + C_F + h * 64 + k0);
;     r.i = *(const u32x4*)(proj + row * NPROJ + C_I + h * 64 + k0);
;     const float* lbv = (const float*)(p.ws + TBL(T_LB, l)) + h * 64 + k0; r.lb0 = *(const f32x4*)lbv; r.lb1 = *(const f32x4*)(lbv + 4);
;     return r;
; }
; template <int WHICH>
; __device__ void phase_mix_dyn(LAS unsigned char* lds, KP& P0, int l0) {
;     ...
;     if (u >= NMIXU) return;
;     HgRaw nxt; { KPtr P_ = P0; asm volatile("" : "+s"(P_.q)); nxt = hg_load<WHICH>(P_, l0, u, tid0); }
.LBB0_687:
	s_cmpk_gt_u32 s13, 0x923
	s_cbranch_scc1 .LBB0_708
	s_mov_b64 s[14:15], s[30:31]
	s_load_dwordx2 s[14:15], s[14:15], 0xe8
	s_add_i32 s12, s13, 0xfffffcf4
	s_mul_i32 s20, s12, 0xaaab
	s_lshr_b32 s20, s20, 18
	v_ashrrev_i32_e32 v2, 3, v100
	v_lshlrev_b32_e32 v0, 3, v100
	s_mul_i32 s21, s20, -6
	s_waitcnt vmcnt(7)
	v_and_b32_e32 v40, 56, v0
	v_lshl_add_u32 v0, s20, 6, v2
	s_waitcnt lgkmcnt(0)
	v_mov_b64_e32 v[8:9], s[14:15]
	s_add_i32 s12, s21, s12
	v_mad_i64_i32 v[8:9], s[20:21], v0, s9, v[8:9]
	s_lshl_b32 s20, s12, 6
	v_readlane_b32 s22, v255, 25
	s_ashr_i32 s21, s20, 31
	s_mul_hi_i32 s12, s22, 0x44800
	s_mul_i32 s22, s22, 0x44800
	s_add_u32 s22, s14, s22
	s_addc_u32 s12, s15, s12
	s_lshl_b64 s[14:15], s[20:21], 2
	v_lshl_add_u64 v[8:9], s[20:21], 1, v[8:9]
	v_lshlrev_b32_e32 v0, 1, v40
	s_add_u32 s14, s22, s14
	v_lshl_add_u64 v[8:9], v[8:9], 0, v[0:1]
	s_addc_u32 s15, s12, s15
	v_lshlrev_b32_e32 v0, 2, v40
	global_load_dwordx4 v[36:39], v[8:9], off offset:768
	global_load_dwordx4 v[24:27], v[8:9], off offset:1536
	v_lshl_add_u64 v[8:9], s[14:15], 0, v[0:1]
	s_mov_b64 s[14:15], 0xef04800
	v_lshl_add_u64 v[10:11], v[8:9], 0, s[14:15]
	v_add_co_u32_e32 v8, vcc, 0xef04000, v8
	v_ashrrev_i32_e32 v3, 31, v2
	s_nop 0
	v_addc_co_u32_e32 v9, vcc, 0, v9, vcc
	global_load_dwordx4 v[32:35], v[8:9], off offset:2048
	global_load_dwordx4 v[28:31], v[10:11], off offset:16
	v_readlane_b32 s23, v255, 26
	s_waitcnt vmcnt(0)
	s_branch .LBB0_691

; template <int WHICH>
; __device__ void phase_mix_dyn(LAS unsigned char* lds, KP& P0, int l0) {
;     ...
;     for (;;) {
;         if (tid0 == 0) { n1 = n2; n2 = (int)__hip_atomic_fetch_add(ctr, 1u, __ATOMIC_RELAXED, __HIP_MEMORY_SCOPE_AGENT); }
;         KPtr P_ = P0; int l = l0; asm volatile("" : "+s"(P_.q), "+s"(l));
;         const HgRaw cur = nxt;
;         if (un < NMIXU) nxt = hg_load<WHICH>(P_, l, un, tid0);
;         if (WHICH == 0) hgrn_a_unit(lds, P_, l, (u - 780) / 6, (u - 780) % 6, cur);
;         else            hgrn_c_unit(lds, P_, l, (u - 780) / 6, (u - 780) % 6, cur);
.LBB0_691:
	s_cmpk_lt_i32 s62, 0x924
	s_cselect_b64 s[22:23], -1, 0
	s_cmpk_gt_i32 s62, 0x923
	v_readlane_b32 s14, v255, 25
	s_cselect_b64 s[20:21], -1, 0
	v_mov_b64_e32 v[8:9], v[36:37]
	v_mov_b64_e32 v[12:13], v[24:25]
	v_mov_b64_e32 v[16:17], v[32:33]
	s_and_saveexec_b64 s[44:45], s[40:41]
	s_cbranch_execz .Lhg_tk_a
	v_mov_b32_e32 v99, v98
	s_nop 0
	global_atomic_add v98, v1, v203, s[6:7] sc0
